# remove per-phase s_setprio flips in the three GEMM main loops
# speedup vs baseline: 1.0079x; 1.0079x over previous
; #define LAS __attribute__((address_space(3)))
;     ...
;     while (u < o_end) {
;         if (u >= o_mout) {
;             int tidm = F.tid; asm volatile("" : "+v"(tidm)); unsigned lo2 = 0; asm volatile("" : "+s"(lo2)); LAS unsigned char* ldsm = F.lds + lo2; unsigned char* wsm = F.p.ws; asm volatile("" : "+s"(wsm));
;             mx::mlstm_out_loop(wsm, (h16*)F.p.out, F.p.ghead + l * 256, u, o_mout, o_end, ntc, ctx_out, head, chain, (volatile LAS unsigned*)(F.lds + MISC_OFF + 320), (volatile LAS int*)(F.lds + MISC_OFF + 256), ldsm, (char*)ldsm, tidm);
;             break;
;         }
;         unsigned nxt = 0u;
;         if (F.tid == 0) nxt = __hip_atomic_fetch_add(head, 1u, RLX_AGENT);
.LBB0_42:
	s_mov_b32 s84, s8
	s_mov_b64 s[0:1], -1
	s_cmp_lt_i32 s8, s96
	s_mov_b64 s[4:5], -1
	s_cbranch_scc0 .LBB0_41
	v_mov_b32_e32 v213, 0
	s_and_saveexec_b64 s[0:1], s[20:21]
	s_cbranch_execz .LBB0_47
	s_mov_b64 s[6:7], exec
	v_mbcnt_lo_u32_b32 v0, s6, 0
	v_mbcnt_hi_u32_b32 v0, s7, v0
	v_cmp_eq_u32_e32 vcc, 0, v0
	s_and_saveexec_b64 s[4:5], vcc
	s_cbranch_execz .LBB0_46
	s_bcnt1_i32_b64 s6, s[6:7]
	v_mov_b32_e32 v2, s6
	global_atomic_add v2, v1, v2, s[62:63] sc0
.LBB0_46:
	s_or_b64 exec, exec, s[4:5]
	s_waitcnt vmcnt(0)
	v_readfirstlane_b32 s4, v2
	s_nop 1
	v_add_u32_e32 v213, s4, v0

; #define LAS __attribute__((address_space(3)))
; #define BAR_LDS() asm volatile("s_waitcnt lgkmcnt(0)\n\ts_barrier" ::: "memory")
;     ...
;         { volatile LAS int* slot = (volatile LAS int*)(F.lds + MISC_OFF + 256);
;           BAR_LDS(); if (F.tid == 0) *slot = (int)nxt; BAR_LDS(); u = __builtin_amdgcn_readfirstlane(*slot); }
.LBB0_372:
	s_waitcnt lgkmcnt(0)
	s_barrier
	s_mov_b64 s[0:1], exec
	s_and_b64 s[4:5], s[0:1], s[20:21]
	v_mov_b32_e32 v247, v211
	s_mov_b64 exec, s[4:5]
	s_cbranch_execz .LBB0_40
	v_mov_b32_e32 v0, s69
	ds_write_b32 v0, v213
	s_branch .LBB0_40

; __device__ __forceinline__ void mlstm_out_loop(unsigned char* ws, h16* Y, const float* ghead  , int u  , const int o_mout, const int o_end, const int ntc, const bool ctx_out, ...
;     ...
;     unsigned tk = 0u; if (tid == 0) tk = __hip_atomic_fetch_add(head, 1u, RLX_AGENT);
;     for (;;) {
;         const unsigned nxt = tk; if (tid == 0) tk = __hip_atomic_fetch_add(head, 1u, RLX_AGENT);
.LBB0_392:
	s_and_saveexec_b64 s[0:1], s[38:39]
	s_cbranch_execz .LBB0_396
	s_mov_b64 s[20:21], exec
	v_mbcnt_lo_u32_b32 v2, s20, 0
	v_mbcnt_hi_u32_b32 v2, s21, v2
	v_cmp_eq_u32_e32 vcc, 0, v2
	s_and_saveexec_b64 s[6:7], vcc
	s_cbranch_execz .LBB0_395
	s_bcnt1_i32_b64 s20, s[20:21]
	v_mov_b32_e32 v4, s20
	v_readlane_b32 s20, v253, 5
	v_readlane_b32 s21, v253, 6
	s_nop 4
	global_atomic_add v4, v1, v4, s[20:21] sc0
.LBB0_395:
	s_or_b64 exec, exec, s[6:7]
	s_waitcnt vmcnt(0)
	v_readfirstlane_b32 s6, v4
	s_nop 1
	v_add_u32_e32 v215, s6, v2

; #define LAS __attribute__((address_space(3)))
; #define VM_WAIT() asm volatile("s_waitcnt vmcnt(0)" ::: "memory")
; __device__ __forceinline__ void mlstm_out_loop(unsigned char* ws, h16* Y, const float* ghead  , int u  , const int o_mout, const int o_end, const int ntc, const bool ctx_out, ...
;     ...
;         if (*acq == 0u) {
;             __syncthreads();
;             if (wid == 0) { unsigned sp = 0; for (;;) { const unsigned f0 = __hip_atomic_load(chain + 64 * lane, RLX_AGENT), f1 = __hip_atomic_load(chain + 64 * (lane + 64), RLX_AGENT);
;                     if (__all(f0 != 0u && f1 != 0u)) break; __builtin_amdgcn_s_sleep(8); if (++sp > (1u << 20)) break; }
;                 __builtin_amdgcn_fence(__ATOMIC_ACQUIRE, "agent"); VM_WAIT(); if (lane == 0) *acq = 1u; }
;             __syncthreads();
;         }
;         if (!have_mn) { mout_load_mn(R, ws, b, h, tc, tid); have_mn = true; }
;         const float m0g = R.m0g, nval = R.nval;
; #pragma unroll
;         for (int j = 0; j < 2; ++j) { const int i = tid + 512 * j, row = i >> 3, c8 = i & 7, sl = row >> 6, r = row & 63;
;             *(LAS u32x4*)(lds + MO_K + sl * 8192 + c8 * 1024 + r * 16) = R.kv[j];
;             *(LAS u32x4*)(lds + MO_V + sl * 8192 + ((c8 >> 2) * 4 + (r >> 4)) * 1024 + (r & 15) * 64 + (c8 & 3) * 16) = R.vv[j];
;             *(LAS u32x4*)(lds + MO_Q + c8 * 2048 + row * 16) = R.qv[j]; }
; #pragma unroll
;         for (int d = 0; d < 2; ++d) *(LAS u32x4*)(lds + MO_CF + d * 8192 + (tid & 7) * 1024 + (tid >> 3) * 16) = R.cfv[d];
.LBB0_400:
	v_mov_b32_e32 v2, s82
	ds_read_b32 v2, v2
	s_waitcnt lgkmcnt(0)
	v_cmp_ne_u32_e32 vcc, 0, v2
	s_cbranch_vccz .LBB0_402
	s_andn2_b64 vcc, exec, s[0:1]
	s_cbranch_vccz .LBB0_411
	s_branch .LBB0_414

; #define LAS __attribute__((address_space(3)))
; __device__ __forceinline__ void mlstm_out_loop(unsigned char* ws, h16* Y, const float* ghead  , int u  , const int o_mout, const int o_end, const int ntc, const bool ctx_out, ...
;     ...
; #pragma unroll
;         for (int j = 0; j < 2; ++j) { const int i = tid + 512 * j, row = i >> 3, c8 = i & 7, sl = row >> 6, r = row & 63;
;             *(LAS u32x4*)(lds + MO_K + sl * 8192 + c8 * 1024 + r * 16) = R.kv[j];
;             *(LAS u32x4*)(lds + MO_V + sl * 8192 + ((c8 >> 2) * 4 + (r >> 4)) * 1024 + (r & 15) * 64 + (c8 & 3) * 16) = R.vv[j];
;             *(LAS u32x4*)(lds + MO_Q + c8 * 2048 + row * 16) = R.qv[j]; }
; #pragma unroll
;         for (int d = 0; d < 2; ++d) *(LAS u32x4*)(lds + MO_CF + d * 8192 + (tid & 7) * 1024 + (tid >> 3) * 16) = R.cfv[d];
.LBB0_414:
	s_andn2_b64 vcc, exec, s[10:11]
	s_waitcnt vmcnt(5)
	ds_write_b128 v183, v[66:69]
	s_waitcnt vmcnt(4)
	ds_write_b128 v184, v[70:73] offset:16384
	s_waitcnt vmcnt(3)
	ds_write_b128 v185, v[74:77]
	s_waitcnt vmcnt(2)
	ds_write_b128 v186, v[78:81]
	s_waitcnt vmcnt(1)
	ds_write_b128 v187, v[82:85] offset:16384
	s_waitcnt vmcnt(0)
	ds_write_b128 v188, v[86:89]
	ds_write_b128 v189, v[90:93]
	ds_write_b128 v189, v[94:97] offset:8192
	s_cbranch_vccz .LBB0_433
	s_and_saveexec_b64 s[0:1], s[38:39]

; #define PG8_STAGE(bufoff, gbase) do { _Pragma("unroll") for (int _i = 0; _i < 2; ++_i) \
;         __builtin_amdgcn_global_load_lds((const unsigned*)((const char*)(gbase) + voffA[_i]), (LAS unsigned*)(lds + (bufoff) + ldsw + _i * 8192), 16, 0, 0); } while (0)
; #define PG8_LDA(dst, b, h) do { _Pragma("unroll") for (int m = 0; m < 4; ++m) _Pragma("unroll") for (int k = 0; k < 2; ++k) dst[m][k] = *(const LAS h16x8*)(lds + PG8_SA(b, h) + aoff + m * 2048 + k * 1024); } while (0)
; #define PG8_LDB(dst, b, h) do { _Pragma("unroll") for (int n = 0; n < 2; ++n) _Pragma("unroll") for (int k = 0; k < 2; ++k) dst[n][k] = *(const LAS h16x8*)(lds + PG8_SB(b, h) + boff + n * 2048 + k * 1024); } while (0)
; #define PG8_LDA1(dst, b) do { if constexpr (!HALFM) PG8_LDA(dst, b, 1); } while (0)
; #define PG8_MMA1(At, B0, B1) do { if constexpr (!HALFM) { PG8_MMA(1, 0, At, B0); PG8_MMA(1, 1, At, B1); } } while (0)
; #define PG8_WAIT_V(n) asm volatile("s_waitcnt vmcnt(" #n ")" ::: "memory")
; #define PG8_WAIT_L(n) asm volatile("s_waitcnt lgkmcnt(" #n ")" ::: "memory")
; #define PG8_BAR __builtin_amdgcn_s_barrier()
; #define PG8_SCHED __builtin_amdgcn_sched_barrier(0)
; template <class Epi, bool ALIGN_EPI, bool SP2, bool BF = false, bool HALFM = false, class Order = StaticOrder>
; __device__ __forceinline__ void gemm_phase(LAS unsigned char* lds, const int tid, const Gemm g, const Order& S, const Epi& E, const bool dry = false) {
;     ...
;         for (int t = 0; t < nt; t += 2) {
;             const bool last = (t == nt - 2);
;             const char* a1 = cA + (size_t)(t + 1) * kstep;
;             const char* a2 = last ? nA : cA + (size_t)(t + 2) * kstep; const char* b2 = last ? nB : cB + (size_t)(t + 2) * kstep;
;             const char* a3 = a2 + kstep; const char* b3 = b2 + kstep;
;             if constexpr (SP2) {
;             PG8_LDB(B0, 0, 0); PG8_LDB(B1, 0, 1); PG8_SCHED; PG8_LDA(At, 0, 0); PG8_STAGE(PG8_SA(1, 1), a1 + hstep);
;             PG8_WAIT_V(8); PG8_WAIT_L(0); PG8_BAR; PG8_MMA(0, 0, At, B0); PG8_MMA(0, 1, At, B1); PG8_BAR; PG8_SCHED;
;             PG8_LDA1(At, 0); PG8_STAGE(PG8_SB(0, 0), b2); PG8_STAGE(PG8_SB(0, 1), b2 + hstep); PG8_STAGE(PG8_SA(0, 0), a2);
;             PG8_WAIT_V(8); PG8_WAIT_L(0); PG8_BAR; PG8_MMA1(At, B0, B1); PG8_BAR; PG8_SCHED;
.LBB0_452:
	v_add_u32_e32 v0, s52, v189
	ds_read_b128 v[18:21], v0
	ds_read_b128 v[22:25], v0 offset:1024
	ds_read_b128 v[26:29], v0 offset:2048
	ds_read_b128 v[30:33], v0 offset:3072
	v_add_u32_e32 v0, s55, v189
	ds_read_b128 v[50:53], v0
	ds_read_b128 v[54:57], v0 offset:1024
	ds_read_b128 v[58:61], v0 offset:2048
	ds_read_b128 v[62:65], v0 offset:3072
	s_add_u32 s38, s2, 0xfffc0080
	s_addc_u32 s39, s3, -1
	s_cmp_eq_u32 s97, 12
	s_cselect_b32 s43, s1, s39
	s_cselect_b32 s42, s5, s38
	s_cselect_b32 s39, s19, s45
	s_cselect_b32 s38, s21, s44
	v_lshl_add_u64 v[222:223], s[2:3], 0, v[168:169]
	s_add_i32 m0, s79, 0xc000
	ds_read_b128 v[172:175], v190
	ds_read_b128 v[176:179], v190 offset:1024
	ds_read_b128 v[192:195], v190 offset:2048
	ds_read_b128 v[196:199], v190 offset:3072
	ds_read_b128 v[200:203], v190 offset:4096
	ds_read_b128 v[204:207], v190 offset:5120
	ds_read_b128 v[214:217], v190 offset:6144
	ds_read_b128 v[218:221], v190 offset:7168
	global_load_lds_dwordx4 v[222:223], off
	v_lshl_add_u64 v[222:223], s[2:3], 0, v[170:171]
	s_add_i32 m0, s79, 0xe000
	s_nop 0
	global_load_lds_dwordx4 v[222:223], off
	s_waitcnt vmcnt(8)
	s_waitcnt lgkmcnt(0)
	s_barrier
	s_waitcnt lgkmcnt(0)
	v_mfma_f32_16x16x32_f16 v[160:163], v[18:21], v[172:175], v[160:163]
	v_mfma_f32_16x16x32_f16 v[156:159], v[26:29], v[172:175], v[156:159]
	v_mfma_f32_16x16x32_f16 v[144:147], v[18:21], v[192:195], v[144:147]
	v_mfma_f32_16x16x32_f16 v[140:143], v[26:29], v[192:195], v[140:143]
	v_mfma_f32_16x16x32_f16 v[126:129], v[18:21], v[200:203], v[126:129]
	v_mfma_f32_16x16x32_f16 v[122:125], v[26:29], v[200:203], v[122:125]
	v_mfma_f32_16x16x32_f16 v[110:113], v[18:21], v[214:217], v[110:113]
	v_mfma_f32_16x16x32_f16 v[106:109], v[26:29], v[214:217], v[106:109]
	v_mfma_f32_16x16x32_f16 v[160:163], v[22:25], v[176:179], v[160:163]
	v_mfma_f32_16x16x32_f16 v[156:159], v[30:33], v[176:179], v[156:159]
	v_mfma_f32_16x16x32_f16 v[144:147], v[22:25], v[196:199], v[144:147]
	v_mfma_f32_16x16x32_f16 v[140:143], v[30:33], v[196:199], v[140:143]
	v_mfma_f32_16x16x32_f16 v[126:129], v[22:25], v[204:207], v[126:129]
	v_mfma_f32_16x16x32_f16 v[122:125], v[30:33], v[204:207], v[122:125]
	v_mfma_f32_16x16x32_f16 v[110:113], v[22:25], v[218:221], v[110:113]
	v_mfma_f32_16x16x32_f16 v[106:109], v[30:33], v[218:221], v[106:109]
	v_mfma_f32_16x16x32_f16 v[152:155], v[50:53], v[172:175], v[152:155]
	v_mfma_f32_16x16x32_f16 v[148:151], v[58:61], v[172:175], v[148:151]
	v_mfma_f32_16x16x32_f16 v[136:139], v[50:53], v[192:195], v[136:139]
	v_mfma_f32_16x16x32_f16 v[132:135], v[58:61], v[192:195], v[132:135]
	v_mfma_f32_16x16x32_f16 v[118:121], v[50:53], v[200:203], v[118:121]
	v_mfma_f32_16x16x32_f16 v[114:117], v[58:61], v[200:203], v[114:117]
	v_mfma_f32_16x16x32_f16 v[102:105], v[50:53], v[214:217], v[102:105]
	v_mfma_f32_16x16x32_f16 v[98:101], v[58:61], v[214:217], v[98:101]
	v_mfma_f32_16x16x32_f16 v[152:155], v[54:57], v[176:179], v[152:155]
	v_mfma_f32_16x16x32_f16 v[148:151], v[62:65], v[176:179], v[148:151]
	v_mfma_f32_16x16x32_f16 v[136:139], v[54:57], v[196:199], v[136:139]
	v_mfma_f32_16x16x32_f16 v[132:135], v[62:65], v[196:199], v[132:135]
	v_mfma_f32_16x16x32_f16 v[118:121], v[54:57], v[204:207], v[118:121]
	v_mfma_f32_16x16x32_f16 v[114:117], v[62:65], v[204:207], v[114:117]
	v_mfma_f32_16x16x32_f16 v[102:105], v[54:57], v[218:221], v[102:105]
	v_mfma_f32_16x16x32_f16 v[98:101], v[62:65], v[218:221], v[98:101]
	s_barrier
	s_mov_b32 m0, s53
	v_lshl_add_u64 v[226:227], s[38:39], 0, v[164:165]
	s_add_u32 vcc_lo, s38, 0x40000
	ds_read_b128 v[172:175], v190 offset:16384
	ds_read_b128 v[176:179], v190 offset:17408
	ds_read_b128 v[192:195], v190 offset:18432
	ds_read_b128 v[196:199], v190 offset:19456
	ds_read_b128 v[200:203], v190 offset:20480
	ds_read_b128 v[204:207], v190 offset:21504
	ds_read_b128 v[214:217], v190 offset:22528
	ds_read_b128 v[218:221], v190 offset:23552
	global_load_lds_dwordx4 v[226:227], off
	v_lshl_add_u64 v[238:239], s[38:39], 0, v[166:167]
	s_mov_b32 m0, s54
	s_addc_u32 vcc_hi, s39, 0
	global_load_lds_dwordx4 v[238:239], off
	v_lshl_add_u64 v[222:223], vcc, 0, v[164:165]
	s_mov_b32 m0, s77
	v_lshl_add_u64 v[248:249], s[42:43], 0, v[164:165]
	global_load_lds_dwordx4 v[222:223], off
	v_lshl_add_u64 v[222:223], vcc, 0, v[166:167]
	s_mov_b32 m0, s78
	v_lshl_add_u64 v[210:211], s[42:43], 0, v[166:167]
	global_load_lds_dwordx4 v[222:223], off
	s_mov_b32 m0, s79
	s_nop 0
	global_load_lds_dwordx4 v[248:249], off
	s_mov_b32 m0, s80
	s_nop 0
	global_load_lds_dwordx4 v[210:211], off
	s_waitcnt vmcnt(8)
	s_waitcnt lgkmcnt(0)
	s_barrier
; #define PG8_STAGE(bufoff, gbase) do { _Pragma("unroll") for (int _i = 0; _i < 2; ++_i) \
;         __builtin_amdgcn_global_load_lds((const unsigned*)((const char*)(gbase) + voffA[_i]), (LAS unsigned*)(lds + (bufoff) + ldsw + _i * 8192), 16, 0, 0); } while (0)
; #define PG8_LDA(dst, b, h) do { _Pragma("unroll") for (int m = 0; m < 4; ++m) _Pragma("unroll") for (int k = 0; k < 2; ++k) dst[m][k] = *(const LAS h16x8*)(lds + PG8_SA(b, h) + aoff + m * 2048 + k * 1024); } while (0)
; #define PG8_LDB(dst, b, h) do { _Pragma("unroll") for (int n = 0; n < 2; ++n) _Pragma("unroll") for (int k = 0; k < 2; ++k) dst[n][k] = *(const LAS h16x8*)(lds + PG8_SB(b, h) + boff + n * 2048 + k * 1024); } while (0)
; #define PG8_MMA1(At, B0, B1) do { if constexpr (!HALFM) { PG8_MMA(1, 0, At, B0); PG8_MMA(1, 1, At, B1); } } while (0)
; #define PG8_WAIT_V(n) asm volatile("s_waitcnt vmcnt(" #n ")" ::: "memory")
; #define PG8_WAIT_L(n) asm volatile("s_waitcnt lgkmcnt(" #n ")" ::: "memory")
; #define PG8_BAR __builtin_amdgcn_s_barrier()
; #define PG8_SCHED __builtin_amdgcn_sched_barrier(0)
; template <class Epi, bool ALIGN_EPI, bool SP2, bool BF = false, bool HALFM = false, class Order = StaticOrder>
; __device__ __forceinline__ void gemm_phase(LAS unsigned char* lds, const int tid, const Gemm g, const Order& S, const Epi& E, const bool dry = false) {
;     ...
;             PG8_WAIT_V(8); PG8_WAIT_L(0); PG8_BAR; PG8_MMA1(At, B0, B1); PG8_BAR; PG8_SCHED;
;             PG8_LDB(B0, 1, 0); PG8_LDB(B1, 1, 1); PG8_SCHED; PG8_LDA(At, 1, 0); PG8_STAGE(PG8_SA(0, 1), a2 + hstep);
;             PG8_WAIT_V(8); PG8_WAIT_L(0); PG8_BAR; PG8_MMA(0, 0, At, B0); PG8_MMA(0, 1, At, B1); PG8_BAR; PG8_SCHED;
	s_waitcnt lgkmcnt(0)
	v_mfma_f32_16x16x32_f16 v[94:97], v[18:21], v[172:175], v[94:97]
	v_mfma_f32_16x16x32_f16 v[90:93], v[26:29], v[172:175], v[90:93]
	v_mfma_f32_16x16x32_f16 v[78:81], v[18:21], v[192:195], v[78:81]
	v_mfma_f32_16x16x32_f16 v[74:77], v[26:29], v[192:195], v[74:77]
	v_mfma_f32_16x16x32_f16 v[46:49], v[18:21], v[200:203], v[46:49]
	v_mfma_f32_16x16x32_f16 v[42:45], v[26:29], v[200:203], v[42:45]
	v_mfma_f32_16x16x32_f16 v[14:17], v[18:21], v[214:217], v[14:17]
	v_mfma_f32_16x16x32_f16 v[10:13], v[26:29], v[214:217], v[10:13]
	v_mfma_f32_16x16x32_f16 v[94:97], v[22:25], v[176:179], v[94:97]
	v_mfma_f32_16x16x32_f16 v[90:93], v[30:33], v[176:179], v[90:93]
	v_mfma_f32_16x16x32_f16 v[78:81], v[22:25], v[196:199], v[78:81]
	v_mfma_f32_16x16x32_f16 v[74:77], v[30:33], v[196:199], v[74:77]
	v_mfma_f32_16x16x32_f16 v[46:49], v[22:25], v[204:207], v[46:49]
	v_mfma_f32_16x16x32_f16 v[42:45], v[30:33], v[204:207], v[42:45]
	v_mfma_f32_16x16x32_f16 v[14:17], v[22:25], v[218:221], v[14:17]
	v_mfma_f32_16x16x32_f16 v[10:13], v[30:33], v[218:221], v[10:13]
	v_mfma_f32_16x16x32_f16 v[38:41], v[50:53], v[200:203], v[38:41]
	v_mfma_f32_16x16x32_f16 v[34:37], v[58:61], v[200:203], v[34:37]
	v_mfma_f32_16x16x32_f16 v[6:9], v[50:53], v[214:217], v[6:9]
	v_mfma_f32_16x16x32_f16 v[2:5], v[58:61], v[214:217], v[2:5]
	v_mfma_f32_16x16x32_f16 v[18:21], v[50:53], v[172:175], v[86:89]
	v_mfma_f32_16x16x32_f16 v[22:25], v[58:61], v[172:175], v[82:85]
	v_mfma_f32_16x16x32_f16 v[26:29], v[50:53], v[192:195], v[70:73]
	v_mfma_f32_16x16x32_f16 v[30:33], v[58:61], v[192:195], v[66:69]
	v_mfma_f32_16x16x32_f16 v[38:41], v[54:57], v[204:207], v[38:41]
	v_mfma_f32_16x16x32_f16 v[34:37], v[62:65], v[204:207], v[34:37]
	v_mfma_f32_16x16x32_f16 v[6:9], v[54:57], v[218:221], v[6:9]
	v_mfma_f32_16x16x32_f16 v[2:5], v[62:65], v[218:221], v[2:5]
	v_mfma_f32_16x16x32_f16 v[18:21], v[54:57], v[176:179], v[18:21]
	v_mfma_f32_16x16x32_f16 v[22:25], v[62:65], v[176:179], v[22:25]
	v_mfma_f32_16x16x32_f16 v[26:29], v[54:57], v[196:199], v[26:29]
	v_mfma_f32_16x16x32_f16 v[30:33], v[62:65], v[196:199], v[30:33]
	s_barrier
	v_add_u32_e32 v0, s85, v189
	ds_read_b128 v[50:53], v0
	ds_read_b128 v[54:57], v0 offset:1024
	ds_read_b128 v[58:61], v0 offset:2048
	ds_read_b128 v[62:65], v0 offset:3072
	v_add_u32_e32 v0, s51, v189
	ds_read_b128 v[172:175], v0
	ds_read_b128 v[176:179], v0 offset:1024
	ds_read_b128 v[192:195], v0 offset:2048
	ds_read_b128 v[196:199], v0 offset:3072
	s_add_u32 s42, s42, 0x40000
	s_addc_u32 s43, s43, 0
	s_mov_b32 m0, s81
	v_lshl_add_u64 v[222:223], s[42:43], 0, v[164:165]
	ds_read_b128 v[66:69], v190 offset:32768
	ds_read_b128 v[70:73], v190 offset:33792
	ds_read_b128 v[82:85], v190 offset:34816
	ds_read_b128 v[86:89], v190 offset:35840
	ds_read_b128 v[200:203], v190 offset:36864
	ds_read_b128 v[204:207], v190 offset:37888
	ds_read_b128 v[214:217], v190 offset:38912
	ds_read_b128 v[218:221], v190 offset:39936
	global_load_lds_dwordx4 v[222:223], off
	v_lshl_add_u64 v[222:223], s[42:43], 0, v[166:167]
	s_mov_b32 m0, s82
	s_nop 0
	global_load_lds_dwordx4 v[222:223], off
	s_waitcnt vmcnt(8)
	s_waitcnt lgkmcnt(0)
	s_barrier
	s_waitcnt lgkmcnt(0)
	v_mfma_f32_16x16x32_f16 v[160:163], v[50:53], v[66:69], v[160:163]
	v_mfma_f32_16x16x32_f16 v[156:159], v[58:61], v[66:69], v[156:159]
	v_mfma_f32_16x16x32_f16 v[144:147], v[50:53], v[82:85], v[144:147]
	v_mfma_f32_16x16x32_f16 v[140:143], v[58:61], v[82:85], v[140:143]
	v_mfma_f32_16x16x32_f16 v[126:129], v[50:53], v[200:203], v[126:129]
	v_mfma_f32_16x16x32_f16 v[122:125], v[58:61], v[200:203], v[122:125]
	v_mfma_f32_16x16x32_f16 v[110:113], v[50:53], v[214:217], v[110:113]
	v_mfma_f32_16x16x32_f16 v[106:109], v[58:61], v[214:217], v[106:109]
	v_mfma_f32_16x16x32_f16 v[160:163], v[54:57], v[70:73], v[160:163]
	v_mfma_f32_16x16x32_f16 v[156:159], v[62:65], v[70:73], v[156:159]
	v_mfma_f32_16x16x32_f16 v[144:147], v[54:57], v[86:89], v[144:147]
	v_mfma_f32_16x16x32_f16 v[140:143], v[62:65], v[86:89], v[140:143]
	v_mfma_f32_16x16x32_f16 v[126:129], v[54:57], v[204:207], v[126:129]
	v_mfma_f32_16x16x32_f16 v[122:125], v[62:65], v[204:207], v[122:125]
	v_mfma_f32_16x16x32_f16 v[110:113], v[54:57], v[218:221], v[110:113]
	v_mfma_f32_16x16x32_f16 v[106:109], v[62:65], v[218:221], v[106:109]
	v_mfma_f32_16x16x32_f16 v[152:155], v[172:175], v[66:69], v[152:155]
	v_mfma_f32_16x16x32_f16 v[66:69], v[192:195], v[66:69], v[148:151]
	v_mfma_f32_16x16x32_f16 v[148:151], v[196:199], v[70:73], v[66:69]
	v_mfma_f32_16x16x32_f16 v[66:69], v[172:175], v[82:85], v[136:139]
	v_mfma_f32_16x16x32_f16 v[136:139], v[176:179], v[86:89], v[66:69]
	v_mfma_f32_16x16x32_f16 v[66:69], v[192:195], v[82:85], v[132:135]
	v_mfma_f32_16x16x32_f16 v[132:135], v[196:199], v[86:89], v[66:69]
	v_mfma_f32_16x16x32_f16 v[66:69], v[172:175], v[200:203], v[118:121]
	v_mfma_f32_16x16x32_f16 v[118:121], v[176:179], v[204:207], v[66:69]
	v_mfma_f32_16x16x32_f16 v[66:69], v[192:195], v[200:203], v[114:117]
	v_mfma_f32_16x16x32_f16 v[114:117], v[196:199], v[204:207], v[66:69]
	v_mfma_f32_16x16x32_f16 v[66:69], v[172:175], v[214:217], v[102:105]
	v_mfma_f32_16x16x32_f16 v[102:105], v[176:179], v[218:221], v[66:69]
	v_mfma_f32_16x16x32_f16 v[66:69], v[192:195], v[214:217], v[98:101]
	v_mfma_f32_16x16x32_f16 v[152:155], v[176:179], v[70:73], v[152:155]
	v_mfma_f32_16x16x32_f16 v[98:101], v[196:199], v[218:221], v[66:69]
	s_barrier
; #define PG8_STAGE(bufoff, gbase) do { _Pragma("unroll") for (int _i = 0; _i < 2; ++_i) \
;         __builtin_amdgcn_global_load_lds((const unsigned*)((const char*)(gbase) + voffA[_i]), (LAS unsigned*)(lds + (bufoff) + ldsw + _i * 8192), 16, 0, 0); } while (0)
; #define PG8_LDA(dst, b, h) do { _Pragma("unroll") for (int m = 0; m < 4; ++m) _Pragma("unroll") for (int k = 0; k < 2; ++k) dst[m][k] = *(const LAS h16x8*)(lds + PG8_SA(b, h) + aoff + m * 2048 + k * 1024); } while (0)
; #define PG8_LDA1(dst, b) do { if constexpr (!HALFM) PG8_LDA(dst, b, 1); } while (0)
; #define PG8_BAR __builtin_amdgcn_s_barrier()
; template <class Epi, bool ALIGN_EPI, bool SP2, bool BF = false, bool HALFM = false, class Order = StaticOrder>
; __device__ __forceinline__ void gemm_phase(LAS unsigned char* lds, const int tid, const Gemm g, const Order& S, const Epi& E, const bool dry = false) {
;     ...
;             PG8_LDA1(At, 1); PG8_STAGE(PG8_SB(1, 0), b3); PG8_STAGE(PG8_SB(1, 1), b3 + hstep); PG8_STAGE(PG8_SA(1, 0), a3);
;             PG8_WAIT_V(8); PG8_WAIT_L(0); PG8_BAR; PG8_MMA1(At, B0, B1); PG8_BAR; PG8_SCHED;
;             } else {
;             PG8_LDB(B0, 0, 0); PG8_SCHED; PG8_LDA(At, 0, 0); PG8_STAGE(PG8_SA(1, 1), a1 + hstep);
;             PG8_WAIT_L(8); PG8_BAR; PG8_WAIT_L(0); PG8_MMA(0, 0, At, B0); PG8_BAR; PG8_SCHED;
;             PG8_LDB(B1, 0, 1); PG8_STAGE(PG8_SB(0, 0), b2);
;             PG8_BAR; PG8_WAIT_L(0); PG8_MMA(0, 1, At, B1); PG8_BAR;
;             PG8_LDA(At, 0, 1); PG8_STAGE(PG8_SA(0, 0), a2);
;             PG8_BAR; PG8_WAIT_L(0); PG8_MMA(1, 0, At, B0); PG8_BAR; PG8_SCHED;
;             PG8_STAGE(PG8_SB(0, 1), b2 + hstep);
;             PG8_WAIT_V(6); PG8_BAR; PG8_MMA(1, 1, At, B1); PG8_BAR;
;             PG8_LDB(B0, 1, 0); PG8_SCHED; PG8_LDA(At, 1, 0); PG8_STAGE(PG8_SA(0, 1), a2 + hstep);
;             PG8_WAIT_L(8); PG8_BAR; PG8_WAIT_L(0); PG8_MMA(0, 0, At, B0); PG8_BAR; PG8_SCHED;
;             PG8_LDB(B1, 1, 1); PG8_STAGE(PG8_SB(1, 0), b3);
;             PG8_BAR; PG8_WAIT_L(0); PG8_MMA(0, 1, At, B1); PG8_BAR;
;             PG8_LDA(At, 1, 1); PG8_STAGE(PG8_SA(1, 0), a3);
;             PG8_BAR; PG8_WAIT_L(0); PG8_MMA(1, 0, At, B0); PG8_BAR; PG8_SCHED;
;             PG8_STAGE(PG8_SB(1, 1), b3 + hstep);
;             PG8_WAIT_V(6); PG8_BAR; PG8_MMA(1, 1, At, B1); PG8_BAR;
;             }
;         }
;         if constexpr (ALIGN_EPI) { if (wr == 0) PG8_BAR; }
	s_mov_b32 m0, s86
	v_lshl_add_u64 v[82:83], v[226:227], 0, s[94:95]
	s_add_u32 s38, s38, 0x40080
	s_nop 0
	ds_read_b128 v[66:69], v190 offset:49152
	ds_read_b128 v[70:73], v190 offset:50176
	ds_read_b128 v[200:203], v190 offset:51200
	ds_read_b128 v[204:207], v190 offset:52224
	ds_read_b128 v[214:217], v190 offset:53248
	ds_read_b128 v[218:221], v190 offset:54272
	ds_read_b128 v[222:225], v190 offset:55296
	ds_read_b128 v[230:233], v190 offset:56320
	global_load_lds_dwordx4 v[82:83], off
	v_lshl_add_u64 v[82:83], v[238:239], 0, s[94:95]
	s_mov_b32 m0, s87
	s_addc_u32 s39, s39, 0
	global_load_lds_dwordx4 v[82:83], off
	v_lshl_add_u64 v[82:83], s[38:39], 0, v[164:165]
	s_mov_b32 m0, s8
	s_nop 0
	global_load_lds_dwordx4 v[82:83], off
	v_lshl_add_u64 v[82:83], s[38:39], 0, v[166:167]
	s_mov_b32 m0, s9
	s_nop 0
	global_load_lds_dwordx4 v[82:83], off
	v_lshl_add_u64 v[82:83], v[248:249], 0, s[94:95]
	s_mov_b32 m0, s76
	s_nop 0
	global_load_lds_dwordx4 v[82:83], off
	v_lshl_add_u64 v[82:83], v[210:211], 0, s[94:95]
	s_mov_b32 m0, s48
	s_nop 0
	global_load_lds_dwordx4 v[82:83], off
	s_waitcnt vmcnt(8)
	s_waitcnt lgkmcnt(0)
	s_barrier
	s_waitcnt lgkmcnt(0)
	v_mfma_f32_16x16x32_f16 v[82:85], v[50:53], v[66:69], v[94:97]
	v_mfma_f32_16x16x32_f16 v[94:97], v[54:57], v[70:73], v[82:85]
	v_mfma_f32_16x16x32_f16 v[82:85], v[58:61], v[66:69], v[90:93]
	v_mfma_f32_16x16x32_f16 v[78:81], v[50:53], v[200:203], v[78:81]
	v_mfma_f32_16x16x32_f16 v[74:77], v[58:61], v[200:203], v[74:77]
	v_mfma_f32_16x16x32_f16 v[46:49], v[50:53], v[214:217], v[46:49]
	v_mfma_f32_16x16x32_f16 v[42:45], v[58:61], v[214:217], v[42:45]
	v_mfma_f32_16x16x32_f16 v[14:17], v[50:53], v[222:225], v[14:17]
	v_mfma_f32_16x16x32_f16 v[10:13], v[58:61], v[222:225], v[10:13]
	v_mfma_f32_16x16x32_f16 v[90:93], v[62:65], v[70:73], v[82:85]
	v_mfma_f32_16x16x32_f16 v[78:81], v[54:57], v[204:207], v[78:81]
	v_mfma_f32_16x16x32_f16 v[74:77], v[62:65], v[204:207], v[74:77]
	v_mfma_f32_16x16x32_f16 v[46:49], v[54:57], v[218:221], v[46:49]
	v_mfma_f32_16x16x32_f16 v[42:45], v[62:65], v[218:221], v[42:45]
	v_mfma_f32_16x16x32_f16 v[14:17], v[54:57], v[230:233], v[14:17]
	v_mfma_f32_16x16x32_f16 v[10:13], v[62:65], v[230:233], v[10:13]
	v_mfma_f32_16x16x32_f16 v[18:21], v[172:175], v[66:69], v[18:21]
	v_mfma_f32_16x16x32_f16 v[86:89], v[176:179], v[70:73], v[18:21]
	v_mfma_f32_16x16x32_f16 v[18:21], v[192:195], v[66:69], v[22:25]
	v_mfma_f32_16x16x32_f16 v[82:85], v[196:199], v[70:73], v[18:21]
	v_mfma_f32_16x16x32_f16 v[18:21], v[172:175], v[200:203], v[26:29]
	v_mfma_f32_16x16x32_f16 v[70:73], v[176:179], v[204:207], v[18:21]
	v_mfma_f32_16x16x32_f16 v[18:21], v[192:195], v[200:203], v[30:33]
	v_mfma_f32_16x16x32_f16 v[66:69], v[196:199], v[204:207], v[18:21]
	v_mfma_f32_16x16x32_f16 v[18:21], v[172:175], v[214:217], v[38:41]
	v_mfma_f32_16x16x32_f16 v[38:41], v[176:179], v[218:221], v[18:21]
	v_mfma_f32_16x16x32_f16 v[18:21], v[192:195], v[214:217], v[34:37]
	v_mfma_f32_16x16x32_f16 v[6:9], v[172:175], v[222:225], v[6:9]
	v_mfma_f32_16x16x32_f16 v[2:5], v[192:195], v[222:225], v[2:5]
	v_mfma_f32_16x16x32_f16 v[34:37], v[196:199], v[218:221], v[18:21]
	v_mfma_f32_16x16x32_f16 v[6:9], v[176:179], v[230:233], v[6:9]
	v_mfma_f32_16x16x32_f16 v[2:5], v[196:199], v[230:233], v[2:5]
	s_barrier
	s_add_i32 s97, s97, 2
	s_add_u32 s2, s2, 0x100
	s_addc_u32 s3, s3, 0
	s_add_u32 s44, s44, 0x100
	s_addc_u32 s45, s45, 0
	s_cmp_gt_u32 s97, 13
	s_cbranch_scc0 .LBB0_452
	s_and_b64 vcc, exec, s[14:15]
	s_cbranch_vccz .LBB0_455
	s_barrier

; #define PG8_STAGE(bufoff, gbase) do { _Pragma("unroll") for (int _i = 0; _i < 2; ++_i) \
;         __builtin_amdgcn_global_load_lds((const unsigned*)((const char*)(gbase) + voffA[_i]), (LAS unsigned*)(lds + (bufoff) + ldsw + _i * 8192), 16, 0, 0); } while (0)
; #define PG8_LDA(dst, b, h) do { _Pragma("unroll") for (int m = 0; m < 4; ++m) _Pragma("unroll") for (int k = 0; k < 2; ++k) dst[m][k] = *(const LAS h16x8*)(lds + PG8_SA(b, h) + aoff + m * 2048 + k * 1024); } while (0)
; #define PG8_LDB(dst, b, h) do { _Pragma("unroll") for (int n = 0; n < 2; ++n) _Pragma("unroll") for (int k = 0; k < 2; ++k) dst[n][k] = *(const LAS h16x8*)(lds + PG8_SB(b, h) + boff + n * 2048 + k * 1024); } while (0)
; #define PG8_LDA1(dst, b) do { if constexpr (!HALFM) PG8_LDA(dst, b, 1); } while (0)
; #define PG8_MMA1(At, B0, B1) do { if constexpr (!HALFM) { PG8_MMA(1, 0, At, B0); PG8_MMA(1, 1, At, B1); } } while (0)
; #define PG8_WAIT_V(n) asm volatile("s_waitcnt vmcnt(" #n ")" ::: "memory")
; #define PG8_WAIT_L(n) asm volatile("s_waitcnt lgkmcnt(" #n ")" ::: "memory")
; #define PG8_BAR __builtin_amdgcn_s_barrier()
; #define PG8_SCHED __builtin_amdgcn_sched_barrier(0)
; template <class Epi, bool ALIGN_EPI, bool SP2, bool BF = false, bool HALFM = false, class Order = StaticOrder>
; __device__ __forceinline__ void gemm_phase(LAS unsigned char* lds, const int tid, const Gemm g, const Order& S, const Epi& E, const bool dry = false) {
;     ...
;             PG8_LDB(B0, 0, 0); PG8_LDB(B1, 0, 1); PG8_SCHED; PG8_LDA(At, 0, 0); PG8_STAGE(PG8_SA(1, 1), a1 + hstep);
;             PG8_WAIT_V(8); PG8_WAIT_L(0); PG8_BAR; PG8_MMA(0, 0, At, B0); PG8_MMA(0, 1, At, B1); PG8_BAR; PG8_SCHED;
;             PG8_LDA1(At, 0); PG8_STAGE(PG8_SB(0, 0), b2); PG8_STAGE(PG8_SB(0, 1), b2 + hstep); PG8_STAGE(PG8_SA(0, 0), a2);
;             PG8_WAIT_V(8); PG8_WAIT_L(0); PG8_BAR; PG8_MMA1(At, B0, B1); PG8_BAR; PG8_SCHED;
.LBB0_504:
	v_add_u32_e32 v11, s16, v10
	ds_read_b128 v[6:9], v11
	ds_read_b128 v[12:15], v11 offset:1024
	ds_read_b128 v[34:37], v11 offset:2048
	ds_read_b128 v[38:41], v11 offset:3072
	v_add_u32_e32 v11, s19, v10
	s_add_u32 s10, s45, s6
	ds_read_b128 v[42:45], v11
	ds_read_b128 v[46:49], v11 offset:1024
	ds_read_b128 v[98:101], v11 offset:2048
	ds_read_b128 v[102:105], v11 offset:3072
	s_addc_u32 s11, s47, s7
	s_add_u32 s10, s10, 0x100
	s_addc_u32 s11, s11, 0
	s_add_u32 s51, s48, s6
	s_addc_u32 s52, s49, s7
	s_cmpk_eq_i32 s6, 0x700
	s_cselect_b32 s13, s9, s11
	s_cselect_b32 s12, s8, s10
	s_cselect_b32 s11, s3, s52
	s_cselect_b32 s10, s2, s51
	v_lshl_add_u64 v[16:17], v[2:3], 0, s[6:7]
	s_add_i32 m0, s22, 0xc000
	ds_read_b128 v[106:109], v0
	ds_read_b128 v[110:113], v0 offset:1024
	ds_read_b128 v[114:117], v0 offset:2048
	ds_read_b128 v[118:121], v0 offset:3072
	ds_read_b128 v[122:125], v0 offset:4096
	ds_read_b128 v[126:129], v0 offset:5120
	ds_read_b128 v[132:135], v0 offset:6144
	ds_read_b128 v[136:139], v0 offset:7168
	global_load_lds_dwordx4 v[16:17], off
	v_lshl_add_u64 v[16:17], v[4:5], 0, s[6:7]
	s_add_i32 m0, s22, 0xe000
	s_nop 0
	global_load_lds_dwordx4 v[16:17], off
	s_waitcnt vmcnt(8)
	s_waitcnt lgkmcnt(0)
	s_barrier
	s_waitcnt lgkmcnt(0)
	v_mfma_f32_16x16x32_f16 v[94:97], v[6:9], v[106:109], v[94:97]
	v_mfma_f32_16x16x32_f16 v[90:93], v[34:37], v[106:109], v[90:93]
	v_mfma_f32_16x16x32_f16 v[78:81], v[6:9], v[114:117], v[78:81]
	v_mfma_f32_16x16x32_f16 v[74:77], v[34:37], v[114:117], v[74:77]
	v_mfma_f32_16x16x32_f16 v[62:65], v[6:9], v[122:125], v[62:65]
	v_mfma_f32_16x16x32_f16 v[58:61], v[34:37], v[122:125], v[58:61]
	v_mfma_f32_16x16x32_f16 v[6:9], v[6:9], v[132:135], v[30:33]
	v_mfma_f32_16x16x32_f16 v[94:97], v[12:15], v[110:113], v[94:97]
	v_mfma_f32_16x16x32_f16 v[90:93], v[38:41], v[110:113], v[90:93]
	v_mfma_f32_16x16x32_f16 v[78:81], v[12:15], v[118:121], v[78:81]
	v_mfma_f32_16x16x32_f16 v[74:77], v[38:41], v[118:121], v[74:77]
	v_mfma_f32_16x16x32_f16 v[62:65], v[12:15], v[126:129], v[62:65]
	v_mfma_f32_16x16x32_f16 v[58:61], v[38:41], v[126:129], v[58:61]
	v_mfma_f32_16x16x32_f16 v[6:9], v[12:15], v[136:139], v[6:9]
	v_mfma_f32_16x16x32_f16 v[12:15], v[34:37], v[132:135], v[26:29]
	v_mfma_f32_16x16x32_f16 v[12:15], v[38:41], v[136:139], v[12:15]
	v_mfma_f32_16x16x32_f16 v[26:29], v[42:45], v[106:109], v[86:89]
	v_mfma_f32_16x16x32_f16 v[34:37], v[46:49], v[110:113], v[26:29]
	v_mfma_f32_16x16x32_f16 v[26:29], v[98:101], v[106:109], v[82:85]
	v_mfma_f32_16x16x32_f16 v[38:41], v[102:105], v[110:113], v[26:29]
	v_mfma_f32_16x16x32_f16 v[26:29], v[42:45], v[114:117], v[70:73]
	v_mfma_f32_16x16x32_f16 v[70:73], v[46:49], v[118:121], v[26:29]
	v_mfma_f32_16x16x32_f16 v[26:29], v[98:101], v[114:117], v[66:69]
	v_mfma_f32_16x16x32_f16 v[66:69], v[102:105], v[118:121], v[26:29]
	v_mfma_f32_16x16x32_f16 v[26:29], v[42:45], v[122:125], v[54:57]
	v_mfma_f32_16x16x32_f16 v[54:57], v[46:49], v[126:129], v[26:29]
	v_mfma_f32_16x16x32_f16 v[26:29], v[98:101], v[122:125], v[50:53]
	v_mfma_f32_16x16x32_f16 v[22:25], v[42:45], v[132:135], v[22:25]
	v_mfma_f32_16x16x32_f16 v[16:19], v[98:101], v[132:135], v[18:21]
	v_mfma_f32_16x16x32_f16 v[50:53], v[102:105], v[126:129], v[26:29]
	v_mfma_f32_16x16x32_f16 v[22:25], v[46:49], v[136:139], v[22:25]
	v_mfma_f32_16x16x32_f16 v[16:19], v[102:105], v[136:139], v[16:19]
	s_barrier
	s_mov_b32 m0, s17
	v_lshl_add_u64 v[144:145], s[10:11], 0, v[164:165]
	s_add_u32 s52, s10, 0x40000
	global_load_lds_dwordx4 v[144:145], off
	v_lshl_add_u64 v[146:147], s[10:11], 0, v[166:167]
	s_mov_b32 m0, s18
	s_addc_u32 s53, s11, 0
	global_load_lds_dwordx4 v[146:147], off
	v_lshl_add_u64 v[20:21], s[52:53], 0, v[164:165]
	s_mov_b32 m0, s20
	v_lshl_add_u64 v[148:149], s[12:13], 0, v[164:165]
	global_load_lds_dwordx4 v[20:21], off
	v_lshl_add_u64 v[20:21], s[52:53], 0, v[166:167]
	s_mov_b32 m0, s21
	v_lshl_add_u64 v[150:151], s[12:13], 0, v[166:167]
	global_load_lds_dwordx4 v[20:21], off
	s_mov_b32 m0, s22
	s_nop 0
	global_load_lds_dwordx4 v[148:149], off
	s_mov_b32 m0, s23
	s_nop 0
	global_load_lds_dwordx4 v[150:151], off
	s_waitcnt vmcnt(8)
	s_waitcnt lgkmcnt(0)
	s_barrier
; #define PG8_STAGE(bufoff, gbase) do { _Pragma("unroll") for (int _i = 0; _i < 2; ++_i) \
;         __builtin_amdgcn_global_load_lds((const unsigned*)((const char*)(gbase) + voffA[_i]), (LAS unsigned*)(lds + (bufoff) + ldsw + _i * 8192), 16, 0, 0); } while (0)
; template <class Epi, bool ALIGN_EPI, bool SP2, bool BF = false, bool HALFM = false, class Order = StaticOrder>
; __device__ __forceinline__ void gemm_phase(LAS unsigned char* lds, const int tid, const Gemm g, const Order& S, const Epi& E, const bool dry = false) {
;     ...
;             PG8_WAIT_V(8); PG8_WAIT_L(0); PG8_BAR; PG8_MMA1(At, B0, B1); PG8_BAR; PG8_SCHED;
;             PG8_LDB(B0, 1, 0); PG8_LDB(B1, 1, 1); PG8_SCHED; PG8_LDA(At, 1, 0); PG8_STAGE(PG8_SA(0, 1), a2 + hstep);
;             PG8_WAIT_V(8); PG8_WAIT_L(0); PG8_BAR; PG8_MMA(0, 0, At, B0); PG8_MMA(0, 1, At, B1); PG8_BAR; PG8_SCHED;
;             PG8_LDA1(At, 1); PG8_STAGE(PG8_SB(1, 0), b3); PG8_STAGE(PG8_SB(1, 1), b3 + hstep); PG8_STAGE(PG8_SA(1, 0), a3);
;             PG8_WAIT_V(8); PG8_WAIT_L(0); PG8_BAR; PG8_MMA1(At, B0, B1); PG8_BAR; PG8_SCHED;
;             } else {
;             PG8_LDB(B0, 0, 0); PG8_SCHED; PG8_LDA(At, 0, 0); PG8_STAGE(PG8_SA(1, 1), a1 + hstep);
;             PG8_WAIT_L(8); PG8_BAR; PG8_WAIT_L(0); PG8_MMA(0, 0, At, B0); PG8_BAR; PG8_SCHED;
;             PG8_LDB(B1, 0, 1); PG8_STAGE(PG8_SB(0, 0), b2);
;             PG8_BAR; PG8_WAIT_L(0); PG8_MMA(0, 1, At, B1); PG8_BAR;
;             PG8_LDA(At, 0, 1); PG8_STAGE(PG8_SA(0, 0), a2);
;             PG8_BAR; PG8_WAIT_L(0); PG8_MMA(1, 0, At, B0); PG8_BAR; PG8_SCHED;
;             PG8_STAGE(PG8_SB(0, 1), b2 + hstep);
;             PG8_WAIT_V(6); PG8_BAR; PG8_MMA(1, 1, At, B1); PG8_BAR;
;             PG8_LDB(B0, 1, 0); PG8_SCHED; PG8_LDA(At, 1, 0); PG8_STAGE(PG8_SA(0, 1), a2 + hstep);
;             PG8_WAIT_L(8); PG8_BAR; PG8_WAIT_L(0); PG8_MMA(0, 0, At, B0); PG8_BAR; PG8_SCHED;
;             PG8_LDB(B1, 1, 1); PG8_STAGE(PG8_SB(1, 0), b3);
;             PG8_BAR; PG8_WAIT_L(0); PG8_MMA(0, 1, At, B1); PG8_BAR;
;             PG8_LDA(At, 1, 1); PG8_STAGE(PG8_SA(1, 0), a3);
;             PG8_BAR; PG8_WAIT_L(0); PG8_MMA(1, 0, At, B0); PG8_BAR; PG8_SCHED;
;             PG8_STAGE(PG8_SB(1, 1), b3 + hstep);
;             PG8_WAIT_V(6); PG8_BAR; PG8_MMA(1, 1, At, B1); PG8_BAR;
;             }
;         }
;         if constexpr (ALIGN_EPI) { if (wr == 0) PG8_BAR; }
	s_barrier
	v_add_u32_e32 v11, s29, v10
	ds_read_b128 v[26:29], v11
	ds_read_b128 v[30:33], v11 offset:1024
	ds_read_b128 v[42:45], v11 offset:2048
	ds_read_b128 v[46:49], v11 offset:3072
	v_add_u32_e32 v11, s42, v10
	ds_read_b128 v[98:101], v11
	ds_read_b128 v[102:105], v11 offset:1024
	ds_read_b128 v[106:109], v11 offset:2048
	ds_read_b128 v[110:113], v11 offset:3072
	s_add_u32 s12, s12, 0x40000
	s_addc_u32 s13, s13, 0
	s_mov_b32 m0, s24
	v_lshl_add_u64 v[20:21], s[12:13], 0, v[164:165]
	ds_read_b128 v[82:85], v0 offset:32768
	ds_read_b128 v[114:117], v0 offset:33792
	ds_read_b128 v[118:121], v0 offset:34816
	ds_read_b128 v[122:125], v0 offset:35840
	ds_read_b128 v[126:129], v0 offset:36864
	ds_read_b128 v[132:135], v0 offset:37888
	ds_read_b128 v[136:139], v0 offset:38912
	ds_read_b128 v[140:143], v0 offset:39936
	global_load_lds_dwordx4 v[20:21], off
	v_lshl_add_u64 v[20:21], s[12:13], 0, v[166:167]
	s_mov_b32 m0, s25
	s_nop 0
	global_load_lds_dwordx4 v[20:21], off
	s_waitcnt vmcnt(8)
	s_waitcnt lgkmcnt(0)
	s_barrier
	s_waitcnt lgkmcnt(0)
	v_mfma_f32_16x16x32_f16 v[86:89], v[26:29], v[82:85], v[94:97]
	v_mfma_f32_16x16x32_f16 v[78:81], v[26:29], v[118:121], v[78:81]
	v_mfma_f32_16x16x32_f16 v[62:65], v[26:29], v[126:129], v[62:65]
	v_mfma_f32_16x16x32_f16 v[6:9], v[26:29], v[136:139], v[6:9]
	v_mfma_f32_16x16x32_f16 v[94:97], v[30:33], v[114:117], v[86:89]
	v_mfma_f32_16x16x32_f16 v[86:89], v[42:45], v[82:85], v[90:93]
	v_mfma_f32_16x16x32_f16 v[78:81], v[30:33], v[122:125], v[78:81]
	v_mfma_f32_16x16x32_f16 v[74:77], v[42:45], v[118:121], v[74:77]
	v_mfma_f32_16x16x32_f16 v[62:65], v[30:33], v[132:135], v[62:65]
	v_mfma_f32_16x16x32_f16 v[58:61], v[42:45], v[126:129], v[58:61]
	v_mfma_f32_16x16x32_f16 v[30:33], v[30:33], v[140:143], v[6:9]
	v_mfma_f32_16x16x32_f16 v[6:9], v[42:45], v[136:139], v[12:15]
	v_mfma_f32_16x16x32_f16 v[90:93], v[46:49], v[114:117], v[86:89]
	v_mfma_f32_16x16x32_f16 v[74:77], v[46:49], v[122:125], v[74:77]
	v_mfma_f32_16x16x32_f16 v[58:61], v[46:49], v[132:135], v[58:61]
	v_mfma_f32_16x16x32_f16 v[26:29], v[46:49], v[140:143], v[6:9]
	v_mfma_f32_16x16x32_f16 v[6:9], v[98:101], v[82:85], v[34:37]
	v_mfma_f32_16x16x32_f16 v[86:89], v[102:105], v[114:117], v[6:9]
	v_mfma_f32_16x16x32_f16 v[6:9], v[106:109], v[82:85], v[38:41]
	v_mfma_f32_16x16x32_f16 v[82:85], v[110:113], v[114:117], v[6:9]
	v_mfma_f32_16x16x32_f16 v[6:9], v[98:101], v[118:121], v[70:73]
	v_mfma_f32_16x16x32_f16 v[70:73], v[102:105], v[122:125], v[6:9]
	v_mfma_f32_16x16x32_f16 v[6:9], v[106:109], v[118:121], v[66:69]
	v_mfma_f32_16x16x32_f16 v[66:69], v[110:113], v[122:125], v[6:9]
	v_mfma_f32_16x16x32_f16 v[6:9], v[98:101], v[126:129], v[54:57]
	v_mfma_f32_16x16x32_f16 v[54:57], v[102:105], v[132:135], v[6:9]
	v_mfma_f32_16x16x32_f16 v[6:9], v[106:109], v[126:129], v[50:53]
	v_mfma_f32_16x16x32_f16 v[50:53], v[110:113], v[132:135], v[6:9]
	v_mfma_f32_16x16x32_f16 v[6:9], v[98:101], v[136:139], v[22:25]
	v_mfma_f32_16x16x32_f16 v[22:25], v[102:105], v[140:143], v[6:9]
	v_mfma_f32_16x16x32_f16 v[6:9], v[106:109], v[136:139], v[16:19]
	v_mfma_f32_16x16x32_f16 v[18:21], v[110:113], v[140:143], v[6:9]
	s_barrier
	s_mov_b32 m0, s36
	s_nop 3
	v_lshl_add_u64 v[6:7], v[144:145], 0, s[94:95]
	s_add_u32 s10, s10, 0x40080
	global_load_lds_dwordx4 v[6:7], off
	v_lshl_add_u64 v[6:7], v[146:147], 0, s[94:95]
	s_mov_b32 m0, s37
	s_addc_u32 s11, s11, 0
	global_load_lds_dwordx4 v[6:7], off
	v_lshl_add_u64 v[6:7], s[10:11], 0, v[164:165]
	s_mov_b32 m0, s43
	s_nop 0
	global_load_lds_dwordx4 v[6:7], off
	v_lshl_add_u64 v[6:7], s[10:11], 0, v[166:167]
	s_mov_b32 m0, s44
	s_nop 0
	global_load_lds_dwordx4 v[6:7], off
	v_lshl_add_u64 v[6:7], v[148:149], 0, s[94:95]
	s_mov_b32 m0, s38
	s_nop 0
	global_load_lds_dwordx4 v[6:7], off
	v_lshl_add_u64 v[6:7], v[150:151], 0, s[94:95]
	s_mov_b32 m0, s39
	s_nop 0
	global_load_lds_dwordx4 v[6:7], off
	s_waitcnt vmcnt(8)
	s_waitcnt lgkmcnt(0)
	s_barrier
	s_barrier
	s_add_i32 s50, s50, 2
	s_add_u32 s6, s6, 0x100
	s_addc_u32 s7, s7, 0
	s_cmp_gt_u32 s50, 13
	s_cbranch_scc0 .LBB0_504
	s_cmpk_lt_u32 s15, 0x100
	s_mov_b64 s[60:61], 0x800
	s_cbranch_scc0 .LBB0_507
	s_barrier

; #define PG8_STAGE(bufoff, gbase) do { _Pragma("unroll") for (int _i = 0; _i < 2; ++_i) \
;         __builtin_amdgcn_global_load_lds((const unsigned*)((const char*)(gbase) + voffA[_i]), (LAS unsigned*)(lds + (bufoff) + ldsw + _i * 8192), 16, 0, 0); } while (0)
; #define PG8_LDA(dst, b, h) do { _Pragma("unroll") for (int m = 0; m < 4; ++m) _Pragma("unroll") for (int k = 0; k < 2; ++k) dst[m][k] = *(const LAS h16x8*)(lds + PG8_SA(b, h) + aoff + m * 2048 + k * 1024); } while (0)
; #define PG8_LDB(dst, b, h) do { _Pragma("unroll") for (int n = 0; n < 2; ++n) _Pragma("unroll") for (int k = 0; k < 2; ++k) dst[n][k] = *(const LAS h16x8*)(lds + PG8_SB(b, h) + boff + n * 2048 + k * 1024); } while (0)
; #define PG8_LDA1(dst, b) do { if constexpr (!HALFM) PG8_LDA(dst, b, 1); } while (0)
; #define PG8_MMA1(At, B0, B1) do { if constexpr (!HALFM) { PG8_MMA(1, 0, At, B0); PG8_MMA(1, 1, At, B1); } } while (0)
; #define PG8_WAIT_V(n) asm volatile("s_waitcnt vmcnt(" #n ")" ::: "memory")
; #define PG8_WAIT_L(n) asm volatile("s_waitcnt lgkmcnt(" #n ")" ::: "memory")
; #define PG8_BAR __builtin_amdgcn_s_barrier()
; #define PG8_SCHED __builtin_amdgcn_sched_barrier(0)
; template <class Epi, bool ALIGN_EPI, bool SP2, bool BF = false, bool HALFM = false, class Order = StaticOrder>
; __device__ __forceinline__ void gemm_phase(LAS unsigned char* lds, const int tid, const Gemm g, const Order& S, const Epi& E, const bool dry = false) {
;     ...
;             PG8_LDB(B0, 0, 0); PG8_LDB(B1, 0, 1); PG8_SCHED; PG8_LDA(At, 0, 0); PG8_STAGE(PG8_SA(1, 1), a1 + hstep);
;             PG8_WAIT_V(8); PG8_WAIT_L(0); PG8_BAR; PG8_MMA(0, 0, At, B0); PG8_MMA(0, 1, At, B1); PG8_BAR; PG8_SCHED;
;             PG8_LDA1(At, 0); PG8_STAGE(PG8_SB(0, 0), b2); PG8_STAGE(PG8_SB(0, 1), b2 + hstep); PG8_STAGE(PG8_SA(0, 0), a2);
;             PG8_WAIT_V(8); PG8_WAIT_L(0); PG8_BAR; PG8_MMA1(At, B0, B1); PG8_BAR; PG8_SCHED;
.LBB0_561:
	v_add_u32_e32 v144, s46, v198
	v_add_u32_e32 v160, s49, v198
	ds_read_b128 v[132:135], v144
	ds_read_b128 v[136:139], v144 offset:1024
	ds_read_b128 v[140:143], v144 offset:2048
	ds_read_b128 v[144:147], v144 offset:3072
	ds_read_b128 v[148:151], v160
	ds_read_b128 v[152:155], v160 offset:1024
	ds_read_b128 v[156:159], v160 offset:2048
	ds_read_b128 v[160:163], v160 offset:3072
	s_add_u32 s38, s36, 0xfffc0080
	s_addc_u32 s39, s37, -1
	s_cmp_eq_u32 s21, 12
	s_cselect_b32 s43, s3, s39
	s_cselect_b32 s42, s5, s38
	s_cselect_b32 s39, s8, s19
	s_cselect_b32 s38, s9, s11
	v_lshl_add_u64 v[194:195], s[36:37], 0, v[168:169]
	s_add_i32 m0, s52, 0xc000
	ds_read_b128 v[170:173], v199
	ds_read_b128 v[174:177], v199 offset:1024
	ds_read_b128 v[178:181], v199 offset:2048
	ds_read_b128 v[182:185], v199 offset:3072
	ds_read_b128 v[186:189], v199 offset:4096
	ds_read_b128 v[190:193], v199 offset:5120
	ds_read_b128 v[200:203], v199 offset:6144
	ds_read_b128 v[204:207], v199 offset:7168
	global_load_lds_dwordx4 v[194:195], off
	v_lshl_add_u64 v[194:195], s[36:37], 0, v[166:167]
	s_add_i32 m0, s52, 0xe000
	s_nop 0
	global_load_lds_dwordx4 v[194:195], off
	s_waitcnt vmcnt(8)
	s_waitcnt lgkmcnt(0)
	s_barrier
	s_waitcnt lgkmcnt(0)
	v_mfma_f32_16x16x32_f16 v[70:73], v[132:135], v[170:173], v[70:73]
	v_mfma_f32_16x16x32_f16 v[66:69], v[140:143], v[170:173], v[66:69]
	v_mfma_f32_16x16x32_f16 v[50:53], v[132:135], v[178:181], v[50:53]
	v_mfma_f32_16x16x32_f16 v[46:49], v[140:143], v[178:181], v[46:49]
	v_mfma_f32_16x16x32_f16 v[54:57], v[132:135], v[186:189], v[54:57]
	v_mfma_f32_16x16x32_f16 v[42:45], v[140:143], v[186:189], v[42:45]
	v_mfma_f32_16x16x32_f16 v[38:41], v[132:135], v[200:203], v[38:41]
	v_mfma_f32_16x16x32_f16 v[34:37], v[140:143], v[200:203], v[34:37]
	v_mfma_f32_16x16x32_f16 v[70:73], v[136:139], v[174:177], v[70:73]
	v_mfma_f32_16x16x32_f16 v[66:69], v[144:147], v[174:177], v[66:69]
	v_mfma_f32_16x16x32_f16 v[50:53], v[136:139], v[182:185], v[50:53]
	v_mfma_f32_16x16x32_f16 v[46:49], v[144:147], v[182:185], v[46:49]
	v_mfma_f32_16x16x32_f16 v[54:57], v[136:139], v[190:193], v[54:57]
	v_mfma_f32_16x16x32_f16 v[42:45], v[144:147], v[190:193], v[42:45]
	v_mfma_f32_16x16x32_f16 v[38:41], v[136:139], v[204:207], v[38:41]
	v_mfma_f32_16x16x32_f16 v[34:37], v[144:147], v[204:207], v[34:37]
	v_mfma_f32_16x16x32_f16 v[126:129], v[148:151], v[170:173], v[126:129]
	v_mfma_f32_16x16x32_f16 v[122:125], v[156:159], v[170:173], v[122:125]
	v_mfma_f32_16x16x32_f16 v[118:121], v[148:151], v[178:181], v[118:121]
	v_mfma_f32_16x16x32_f16 v[114:117], v[156:159], v[178:181], v[114:117]
	v_mfma_f32_16x16x32_f16 v[110:113], v[148:151], v[186:189], v[110:113]
	v_mfma_f32_16x16x32_f16 v[106:109], v[156:159], v[186:189], v[106:109]
	v_mfma_f32_16x16x32_f16 v[102:105], v[148:151], v[200:203], v[102:105]
	v_mfma_f32_16x16x32_f16 v[98:101], v[156:159], v[200:203], v[98:101]
	v_mfma_f32_16x16x32_f16 v[126:129], v[152:155], v[174:177], v[126:129]
	v_mfma_f32_16x16x32_f16 v[122:125], v[160:163], v[174:177], v[122:125]
	v_mfma_f32_16x16x32_f16 v[118:121], v[152:155], v[182:185], v[118:121]
	v_mfma_f32_16x16x32_f16 v[114:117], v[160:163], v[182:185], v[114:117]
	v_mfma_f32_16x16x32_f16 v[110:113], v[152:155], v[190:193], v[110:113]
	v_mfma_f32_16x16x32_f16 v[106:109], v[160:163], v[190:193], v[106:109]
	v_mfma_f32_16x16x32_f16 v[102:105], v[152:155], v[204:207], v[102:105]
	v_mfma_f32_16x16x32_f16 v[98:101], v[160:163], v[204:207], v[98:101]
	s_barrier
	s_mov_b32 m0, s47
	v_lshl_add_u64 v[194:195], s[38:39], 0, v[0:1]
	s_add_u32 vcc_lo, s38, 0x40000
	ds_read_b128 v[170:173], v199 offset:16384
	ds_read_b128 v[174:177], v199 offset:17408
	ds_read_b128 v[178:181], v199 offset:18432
	ds_read_b128 v[182:185], v199 offset:19456
	ds_read_b128 v[186:189], v199 offset:20480
	ds_read_b128 v[190:193], v199 offset:21504
	ds_read_b128 v[200:203], v199 offset:22528
	ds_read_b128 v[204:207], v199 offset:23552
	global_load_lds_dwordx4 v[194:195], off
	v_lshl_add_u64 v[214:215], s[38:39], 0, v[164:165]
	s_mov_b32 m0, s48
	s_addc_u32 vcc_hi, s39, 0
	global_load_lds_dwordx4 v[214:215], off
	v_lshl_add_u64 v[216:217], vcc, 0, v[0:1]
	s_mov_b32 m0, s50
	v_lshl_add_u64 v[218:219], s[42:43], 0, v[164:165]
	global_load_lds_dwordx4 v[216:217], off
	v_lshl_add_u64 v[216:217], vcc, 0, v[164:165]
	s_mov_b32 m0, s51
	s_nop 0
	global_load_lds_dwordx4 v[216:217], off
	v_lshl_add_u64 v[216:217], s[42:43], 0, v[0:1]
	s_mov_b32 m0, s52
	s_nop 0
	global_load_lds_dwordx4 v[216:217], off
	s_mov_b32 m0, s53
	s_nop 0
	global_load_lds_dwordx4 v[218:219], off
	s_waitcnt vmcnt(8)
	s_waitcnt lgkmcnt(0)
	s_barrier
; #define PG8_STAGE(bufoff, gbase) do { _Pragma("unroll") for (int _i = 0; _i < 2; ++_i) \
;         __builtin_amdgcn_global_load_lds((const unsigned*)((const char*)(gbase) + voffA[_i]), (LAS unsigned*)(lds + (bufoff) + ldsw + _i * 8192), 16, 0, 0); } while (0)
; #define PG8_LDA(dst, b, h) do { _Pragma("unroll") for (int m = 0; m < 4; ++m) _Pragma("unroll") for (int k = 0; k < 2; ++k) dst[m][k] = *(const LAS h16x8*)(lds + PG8_SA(b, h) + aoff + m * 2048 + k * 1024); } while (0)
; #define PG8_LDB(dst, b, h) do { _Pragma("unroll") for (int n = 0; n < 2; ++n) _Pragma("unroll") for (int k = 0; k < 2; ++k) dst[n][k] = *(const LAS h16x8*)(lds + PG8_SB(b, h) + boff + n * 2048 + k * 1024); } while (0)
; #define PG8_MMA1(At, B0, B1) do { if constexpr (!HALFM) { PG8_MMA(1, 0, At, B0); PG8_MMA(1, 1, At, B1); } } while (0)
; #define PG8_WAIT_V(n) asm volatile("s_waitcnt vmcnt(" #n ")" ::: "memory")
; #define PG8_WAIT_L(n) asm volatile("s_waitcnt lgkmcnt(" #n ")" ::: "memory")
; #define PG8_BAR __builtin_amdgcn_s_barrier()
; #define PG8_SCHED __builtin_amdgcn_sched_barrier(0)
; template <class Epi, bool ALIGN_EPI, bool SP2, bool BF = false, bool HALFM = false, class Order = StaticOrder>
; __device__ __forceinline__ void gemm_phase(LAS unsigned char* lds, const int tid, const Gemm g, const Order& S, const Epi& E, const bool dry = false) {
;     ...
;             PG8_WAIT_V(8); PG8_WAIT_L(0); PG8_BAR; PG8_MMA1(At, B0, B1); PG8_BAR; PG8_SCHED;
;             PG8_LDB(B0, 1, 0); PG8_LDB(B1, 1, 1); PG8_SCHED; PG8_LDA(At, 1, 0); PG8_STAGE(PG8_SA(0, 1), a2 + hstep);
;             PG8_WAIT_V(8); PG8_WAIT_L(0); PG8_BAR; PG8_MMA(0, 0, At, B0); PG8_MMA(0, 1, At, B1); PG8_BAR; PG8_SCHED;
	s_waitcnt lgkmcnt(0)
	v_mfma_f32_16x16x32_f16 v[30:33], v[132:135], v[170:173], v[30:33]
	v_mfma_f32_16x16x32_f16 v[26:29], v[140:143], v[170:173], v[26:29]
	v_mfma_f32_16x16x32_f16 v[22:25], v[132:135], v[178:181], v[22:25]
	v_mfma_f32_16x16x32_f16 v[18:21], v[140:143], v[178:181], v[18:21]
	v_mfma_f32_16x16x32_f16 v[14:17], v[132:135], v[186:189], v[14:17]
	v_mfma_f32_16x16x32_f16 v[10:13], v[140:143], v[186:189], v[10:13]
	v_mfma_f32_16x16x32_f16 v[6:9], v[132:135], v[200:203], v[6:9]
	v_mfma_f32_16x16x32_f16 v[2:5], v[140:143], v[200:203], v[2:5]
	v_mfma_f32_16x16x32_f16 v[30:33], v[136:139], v[174:177], v[30:33]
	v_mfma_f32_16x16x32_f16 v[26:29], v[144:147], v[174:177], v[26:29]
	v_mfma_f32_16x16x32_f16 v[22:25], v[136:139], v[182:185], v[22:25]
	v_mfma_f32_16x16x32_f16 v[18:21], v[144:147], v[182:185], v[18:21]
	v_mfma_f32_16x16x32_f16 v[14:17], v[136:139], v[190:193], v[14:17]
	v_mfma_f32_16x16x32_f16 v[10:13], v[144:147], v[190:193], v[10:13]
	v_mfma_f32_16x16x32_f16 v[6:9], v[136:139], v[204:207], v[6:9]
	v_mfma_f32_16x16x32_f16 v[2:5], v[144:147], v[204:207], v[2:5]
	v_mfma_f32_16x16x32_f16 v[94:97], v[148:151], v[170:173], v[94:97]
	v_mfma_f32_16x16x32_f16 v[90:93], v[156:159], v[170:173], v[90:93]
	v_mfma_f32_16x16x32_f16 v[86:89], v[148:151], v[178:181], v[86:89]
	v_mfma_f32_16x16x32_f16 v[82:85], v[156:159], v[178:181], v[82:85]
	v_mfma_f32_16x16x32_f16 v[78:81], v[148:151], v[186:189], v[78:81]
	v_mfma_f32_16x16x32_f16 v[74:77], v[156:159], v[186:189], v[74:77]
	v_mfma_f32_16x16x32_f16 v[62:65], v[148:151], v[200:203], v[62:65]
	v_mfma_f32_16x16x32_f16 v[58:61], v[156:159], v[200:203], v[58:61]
	v_mfma_f32_16x16x32_f16 v[94:97], v[152:155], v[174:177], v[94:97]
	v_mfma_f32_16x16x32_f16 v[90:93], v[160:163], v[174:177], v[90:93]
	v_mfma_f32_16x16x32_f16 v[86:89], v[152:155], v[182:185], v[86:89]
	v_mfma_f32_16x16x32_f16 v[82:85], v[160:163], v[182:185], v[82:85]
	v_mfma_f32_16x16x32_f16 v[78:81], v[152:155], v[190:193], v[78:81]
	v_mfma_f32_16x16x32_f16 v[74:77], v[160:163], v[190:193], v[74:77]
	v_mfma_f32_16x16x32_f16 v[62:65], v[152:155], v[204:207], v[62:65]
	v_mfma_f32_16x16x32_f16 v[58:61], v[160:163], v[204:207], v[58:61]
	s_barrier
	v_add_u32_e32 v144, s79, v198
	v_add_u32_e32 v160, s84, v198
	ds_read_b128 v[132:135], v144
	ds_read_b128 v[136:139], v144 offset:1024
	ds_read_b128 v[140:143], v144 offset:2048
	ds_read_b128 v[144:147], v144 offset:3072
	ds_read_b128 v[148:151], v160
	ds_read_b128 v[152:155], v160 offset:1024
	ds_read_b128 v[156:159], v160 offset:2048
	ds_read_b128 v[160:163], v160 offset:3072
	s_add_u32 s42, s42, 0x40000
	s_addc_u32 s43, s43, 0
	s_mov_b32 m0, s54
	v_lshl_add_u64 v[220:221], s[42:43], 0, v[0:1]
	ds_read_b128 v[170:173], v199 offset:32768
	ds_read_b128 v[174:177], v199 offset:33792
	ds_read_b128 v[178:181], v199 offset:34816
	ds_read_b128 v[182:185], v199 offset:35840
	ds_read_b128 v[186:189], v199 offset:36864
	ds_read_b128 v[190:193], v199 offset:37888
	ds_read_b128 v[200:203], v199 offset:38912
	ds_read_b128 v[204:207], v199 offset:39936
	global_load_lds_dwordx4 v[220:221], off
	v_lshl_add_u64 v[220:221], s[42:43], 0, v[164:165]
	s_mov_b32 m0, s55
	s_nop 0
	global_load_lds_dwordx4 v[220:221], off
	s_waitcnt vmcnt(8)
	s_waitcnt lgkmcnt(0)
	s_barrier
	s_waitcnt lgkmcnt(0)
	v_mfma_f32_16x16x32_f16 v[70:73], v[132:135], v[170:173], v[70:73]
	v_mfma_f32_16x16x32_f16 v[66:69], v[140:143], v[170:173], v[66:69]
	v_mfma_f32_16x16x32_f16 v[50:53], v[132:135], v[178:181], v[50:53]
	v_mfma_f32_16x16x32_f16 v[46:49], v[140:143], v[178:181], v[46:49]
	v_mfma_f32_16x16x32_f16 v[54:57], v[132:135], v[186:189], v[54:57]
	v_mfma_f32_16x16x32_f16 v[42:45], v[140:143], v[186:189], v[42:45]
	v_mfma_f32_16x16x32_f16 v[38:41], v[132:135], v[200:203], v[38:41]
	v_mfma_f32_16x16x32_f16 v[34:37], v[140:143], v[200:203], v[34:37]
	v_mfma_f32_16x16x32_f16 v[70:73], v[136:139], v[174:177], v[70:73]
	v_mfma_f32_16x16x32_f16 v[66:69], v[144:147], v[174:177], v[66:69]
	v_mfma_f32_16x16x32_f16 v[50:53], v[136:139], v[182:185], v[50:53]
	v_mfma_f32_16x16x32_f16 v[46:49], v[144:147], v[182:185], v[46:49]
	v_mfma_f32_16x16x32_f16 v[54:57], v[136:139], v[190:193], v[54:57]
	v_mfma_f32_16x16x32_f16 v[42:45], v[144:147], v[190:193], v[42:45]
	v_mfma_f32_16x16x32_f16 v[38:41], v[136:139], v[204:207], v[38:41]
	v_mfma_f32_16x16x32_f16 v[34:37], v[144:147], v[204:207], v[34:37]
	v_mfma_f32_16x16x32_f16 v[126:129], v[148:151], v[170:173], v[126:129]
	v_mfma_f32_16x16x32_f16 v[122:125], v[156:159], v[170:173], v[122:125]
	v_mfma_f32_16x16x32_f16 v[118:121], v[148:151], v[178:181], v[118:121]
	v_mfma_f32_16x16x32_f16 v[114:117], v[156:159], v[178:181], v[114:117]
	v_mfma_f32_16x16x32_f16 v[110:113], v[148:151], v[186:189], v[110:113]
	v_mfma_f32_16x16x32_f16 v[106:109], v[156:159], v[186:189], v[106:109]
	v_mfma_f32_16x16x32_f16 v[102:105], v[148:151], v[200:203], v[102:105]
	v_mfma_f32_16x16x32_f16 v[98:101], v[156:159], v[200:203], v[98:101]
	v_mfma_f32_16x16x32_f16 v[126:129], v[152:155], v[174:177], v[126:129]
	v_mfma_f32_16x16x32_f16 v[122:125], v[160:163], v[174:177], v[122:125]
	v_mfma_f32_16x16x32_f16 v[118:121], v[152:155], v[182:185], v[118:121]
	v_mfma_f32_16x16x32_f16 v[114:117], v[160:163], v[182:185], v[114:117]
	v_mfma_f32_16x16x32_f16 v[110:113], v[152:155], v[190:193], v[110:113]
	v_mfma_f32_16x16x32_f16 v[106:109], v[160:163], v[190:193], v[106:109]
	v_mfma_f32_16x16x32_f16 v[102:105], v[152:155], v[204:207], v[102:105]
	v_mfma_f32_16x16x32_f16 v[98:101], v[160:163], v[204:207], v[98:101]
	s_barrier
; #define PG8_STAGE(bufoff, gbase) do { _Pragma("unroll") for (int _i = 0; _i < 2; ++_i) \
;         __builtin_amdgcn_global_load_lds((const unsigned*)((const char*)(gbase) + voffA[_i]), (LAS unsigned*)(lds + (bufoff) + ldsw + _i * 8192), 16, 0, 0); } while (0)
; #define PG8_LDA(dst, b, h) do { _Pragma("unroll") for (int m = 0; m < 4; ++m) _Pragma("unroll") for (int k = 0; k < 2; ++k) dst[m][k] = *(const LAS h16x8*)(lds + PG8_SA(b, h) + aoff + m * 2048 + k * 1024); } while (0)
; #define PG8_LDA1(dst, b) do { if constexpr (!HALFM) PG8_LDA(dst, b, 1); } while (0)
; #define PG8_BAR __builtin_amdgcn_s_barrier()
; template <class Epi, bool ALIGN_EPI, bool SP2, bool BF = false, bool HALFM = false, class Order = StaticOrder>
; __device__ __forceinline__ void gemm_phase(LAS unsigned char* lds, const int tid, const Gemm g, const Order& S, const Epi& E, const bool dry = false) {
;     ...
;             PG8_LDA1(At, 1); PG8_STAGE(PG8_SB(1, 0), b3); PG8_STAGE(PG8_SB(1, 1), b3 + hstep); PG8_STAGE(PG8_SA(1, 0), a3);
;             PG8_WAIT_V(8); PG8_WAIT_L(0); PG8_BAR; PG8_MMA1(At, B0, B1); PG8_BAR; PG8_SCHED;
;             } else {
;             PG8_LDB(B0, 0, 0); PG8_SCHED; PG8_LDA(At, 0, 0); PG8_STAGE(PG8_SA(1, 1), a1 + hstep);
;             PG8_WAIT_L(8); PG8_BAR; PG8_WAIT_L(0); PG8_MMA(0, 0, At, B0); PG8_BAR; PG8_SCHED;
;             PG8_LDB(B1, 0, 1); PG8_STAGE(PG8_SB(0, 0), b2);
;             PG8_BAR; PG8_WAIT_L(0); PG8_MMA(0, 1, At, B1); PG8_BAR;
;             PG8_LDA(At, 0, 1); PG8_STAGE(PG8_SA(0, 0), a2);
;             PG8_BAR; PG8_WAIT_L(0); PG8_MMA(1, 0, At, B0); PG8_BAR; PG8_SCHED;
;             PG8_STAGE(PG8_SB(0, 1), b2 + hstep);
;             PG8_WAIT_V(6); PG8_BAR; PG8_MMA(1, 1, At, B1); PG8_BAR;
;             PG8_LDB(B0, 1, 0); PG8_SCHED; PG8_LDA(At, 1, 0); PG8_STAGE(PG8_SA(0, 1), a2 + hstep);
;             PG8_WAIT_L(8); PG8_BAR; PG8_WAIT_L(0); PG8_MMA(0, 0, At, B0); PG8_BAR; PG8_SCHED;
;             PG8_LDB(B1, 1, 1); PG8_STAGE(PG8_SB(1, 0), b3);
;             PG8_BAR; PG8_WAIT_L(0); PG8_MMA(0, 1, At, B1); PG8_BAR;
;             PG8_LDA(At, 1, 1); PG8_STAGE(PG8_SA(1, 0), a3);
;             PG8_BAR; PG8_WAIT_L(0); PG8_MMA(1, 0, At, B0); PG8_BAR; PG8_SCHED;
;             PG8_STAGE(PG8_SB(1, 1), b3 + hstep);
;             PG8_WAIT_V(6); PG8_BAR; PG8_MMA(1, 1, At, B1); PG8_BAR;
;             }
;         }
;         if constexpr (ALIGN_EPI) { if (wr == 0) PG8_BAR; }
	s_mov_b32 m0, s80
	v_lshl_add_u64 v[194:195], v[194:195], 0, s[94:95]
	s_add_u32 s38, s38, 0x40080
	ds_read_b128 v[170:173], v199 offset:49152
	ds_read_b128 v[174:177], v199 offset:50176
	ds_read_b128 v[178:181], v199 offset:51200
	ds_read_b128 v[182:185], v199 offset:52224
	ds_read_b128 v[186:189], v199 offset:53248
	ds_read_b128 v[190:193], v199 offset:54272
	ds_read_b128 v[200:203], v199 offset:55296
	ds_read_b128 v[204:207], v199 offset:56320
	global_load_lds_dwordx4 v[194:195], off
	v_lshl_add_u64 v[194:195], v[214:215], 0, s[94:95]
	s_mov_b32 m0, s81
	s_addc_u32 s39, s39, 0
	global_load_lds_dwordx4 v[194:195], off
	v_lshl_add_u64 v[194:195], s[38:39], 0, v[0:1]
	s_mov_b32 m0, s85
	s_nop 0
	global_load_lds_dwordx4 v[194:195], off
	v_lshl_add_u64 v[194:195], s[38:39], 0, v[164:165]
	s_mov_b32 m0, s86
	s_nop 0
	global_load_lds_dwordx4 v[194:195], off
	v_lshl_add_u64 v[194:195], v[216:217], 0, s[94:95]
	s_mov_b32 m0, s82
	s_nop 0
	global_load_lds_dwordx4 v[194:195], off
	v_lshl_add_u64 v[194:195], v[218:219], 0, s[94:95]
	s_mov_b32 m0, s83
	s_nop 0
	global_load_lds_dwordx4 v[194:195], off
	s_waitcnt vmcnt(8)
	s_waitcnt lgkmcnt(0)
	s_barrier
	s_waitcnt lgkmcnt(0)
	v_mfma_f32_16x16x32_f16 v[30:33], v[132:135], v[170:173], v[30:33]
	v_mfma_f32_16x16x32_f16 v[26:29], v[140:143], v[170:173], v[26:29]
	v_mfma_f32_16x16x32_f16 v[22:25], v[132:135], v[178:181], v[22:25]
	v_mfma_f32_16x16x32_f16 v[18:21], v[140:143], v[178:181], v[18:21]
	v_mfma_f32_16x16x32_f16 v[14:17], v[132:135], v[186:189], v[14:17]
	v_mfma_f32_16x16x32_f16 v[10:13], v[140:143], v[186:189], v[10:13]
	v_mfma_f32_16x16x32_f16 v[6:9], v[132:135], v[200:203], v[6:9]
	v_mfma_f32_16x16x32_f16 v[2:5], v[140:143], v[200:203], v[2:5]
	v_mfma_f32_16x16x32_f16 v[30:33], v[136:139], v[174:177], v[30:33]
	v_mfma_f32_16x16x32_f16 v[26:29], v[144:147], v[174:177], v[26:29]
	v_mfma_f32_16x16x32_f16 v[22:25], v[136:139], v[182:185], v[22:25]
	v_mfma_f32_16x16x32_f16 v[18:21], v[144:147], v[182:185], v[18:21]
	v_mfma_f32_16x16x32_f16 v[14:17], v[136:139], v[190:193], v[14:17]
	v_mfma_f32_16x16x32_f16 v[10:13], v[144:147], v[190:193], v[10:13]
	v_mfma_f32_16x16x32_f16 v[6:9], v[136:139], v[204:207], v[6:9]
	v_mfma_f32_16x16x32_f16 v[2:5], v[144:147], v[204:207], v[2:5]
	v_mfma_f32_16x16x32_f16 v[94:97], v[148:151], v[170:173], v[94:97]
	v_mfma_f32_16x16x32_f16 v[90:93], v[156:159], v[170:173], v[90:93]
	v_mfma_f32_16x16x32_f16 v[86:89], v[148:151], v[178:181], v[86:89]
	v_mfma_f32_16x16x32_f16 v[82:85], v[156:159], v[178:181], v[82:85]
	v_mfma_f32_16x16x32_f16 v[78:81], v[148:151], v[186:189], v[78:81]
	v_mfma_f32_16x16x32_f16 v[74:77], v[156:159], v[186:189], v[74:77]
	v_mfma_f32_16x16x32_f16 v[62:65], v[148:151], v[200:203], v[62:65]
	v_mfma_f32_16x16x32_f16 v[58:61], v[156:159], v[200:203], v[58:61]
	v_mfma_f32_16x16x32_f16 v[94:97], v[152:155], v[174:177], v[94:97]
	v_mfma_f32_16x16x32_f16 v[90:93], v[160:163], v[174:177], v[90:93]
	v_mfma_f32_16x16x32_f16 v[86:89], v[152:155], v[182:185], v[86:89]
	v_mfma_f32_16x16x32_f16 v[82:85], v[160:163], v[182:185], v[82:85]
	v_mfma_f32_16x16x32_f16 v[78:81], v[152:155], v[190:193], v[78:81]
	v_mfma_f32_16x16x32_f16 v[74:77], v[160:163], v[190:193], v[74:77]
	v_mfma_f32_16x16x32_f16 v[62:65], v[152:155], v[204:207], v[62:65]
	v_mfma_f32_16x16x32_f16 v[58:61], v[160:163], v[204:207], v[58:61]
	s_barrier
	s_add_i32 s21, s21, 2
	s_add_u32 s11, s11, 0x100
	s_addc_u32 s19, s19, 0
	s_add_u32 s36, s36, 0x100
	s_addc_u32 s37, s37, 0
	s_cmp_gt_u32 s21, 13
	s_cbranch_scc0 .LBB0_561
	s_and_b64 vcc, exec, s[12:13]
	s_cbranch_vccz .LBB0_564
	s_barrier
